# NA first-half bias: each group of four is consumed one group later behind a counted lgkmcnt(8) instead of a full LDS drain; last group after the second half's ladder
# speedup vs baseline: 1.0104x; 1.0104x over previous
.LBB0_1705:
	s_add_i32 s90, s14, 2
	v_add_u32_e32 v0, s2, v231
	ds_read_b64_tr_b16 v[194:195], v0 offset:24576
	ds_read_b64_tr_b16 v[196:197], v0 offset:25088
	s_waitcnt lgkmcnt(9)
	v_mfma_f32_32x32x16_bf16 v[96:111], v[190:193], v[142:145], 0
	v_add_f32_e32 v2, v64, v65
	v_add_f32_e32 v2, v66, v2
	v_add_f32_e32 v2, v67, v2
	v_add_f32_e32 v2, v68, v2
	v_add_f32_e32 v2, v69, v2
	v_cvt_pk_bf16_f32 v158, v64, v65
	v_cvt_pk_bf16_f32 v159, v66, v67
	ds_read_b64_tr_b16 v[10:11], v0 offset:28672
	ds_read_b64_tr_b16 v[12:13], v0 offset:29184
	s_waitcnt lgkmcnt(10)
	v_mfma_f32_32x32x16_bf16 v[114:129], v[182:185], v[142:145], 0
	v_add_f32_e32 v2, v70, v2
	v_add_f32_e32 v2, v71, v2
	v_add_f32_e32 v2, v72, v2
	v_add_f32_e32 v6, v73, v2
	v_cvt_pk_bf16_f32 v160, v68, v69
	v_cvt_pk_bf16_f32 v161, v70, v71
	ds_read_b64_tr_b16 v[2:3], v0 offset:25600
	ds_read_b64_tr_b16 v[4:5], v0 offset:26112
	s_waitcnt lgkmcnt(11)
	v_mfma_f32_32x32x16_bf16 v[96:111], v[186:189], v[138:141], v[96:111]
	v_add_f32_e32 v6, v74, v6
	v_add_f32_e32 v6, v75, v6
	v_add_f32_e32 v6, v76, v6
	v_add_f32_e32 v14, v77, v6
	v_cvt_pk_bf16_f32 v154, v72, v73
	v_cvt_pk_bf16_f32 v155, v74, v75
	ds_read_b64_tr_b16 v[6:7], v0 offset:29696
	ds_read_b64_tr_b16 v[8:9], v0 offset:30208
	s_waitcnt lgkmcnt(12)
	v_mfma_f32_32x32x16_bf16 v[114:129], v[178:181], v[138:141], v[114:129]
	v_add_f32_e32 v14, v78, v14
	v_add_f32_e32 v14, v79, v14
	v_add_f32_e32 v14, v80, v14
	v_add_f32_e32 v14, v81, v14
	v_cvt_pk_bf16_f32 v156, v76, v77
	v_cvt_pk_bf16_f32 v157, v78, v79
	ds_read_b64_tr_b16 v[178:179], v0 offset:26624
	ds_read_b64_tr_b16 v[180:181], v0 offset:27136
	s_waitcnt lgkmcnt(13)
	v_mfma_f32_32x32x16_bf16 v[96:111], v[174:177], v[134:137], v[96:111]
	v_add_f32_e32 v14, v82, v14
	v_add_f32_e32 v14, v83, v14
	v_add_f32_e32 v14, v84, v14
	v_add_f32_e32 v14, v85, v14
	v_cvt_pk_bf16_f32 v150, v80, v81
	v_cvt_pk_bf16_f32 v151, v82, v83
	ds_read_b64_tr_b16 v[174:175], v0 offset:30720
	ds_read_b64_tr_b16 v[176:177], v0 offset:31232
	s_waitcnt lgkmcnt(14)
	v_mfma_f32_32x32x16_bf16 v[114:129], v[170:173], v[134:137], v[114:129]
	v_add_f32_e32 v14, v86, v14
	v_add_f32_e32 v14, v87, v14
	v_add_f32_e32 v14, v88, v14
	v_add_f32_e32 v14, v89, v14
	v_cvt_pk_bf16_f32 v152, v84, v85
	v_cvt_pk_bf16_f32 v153, v86, v87
	ds_read_b64_tr_b16 v[170:171], v0 offset:27648
	ds_read_b64_tr_b16 v[172:173], v0 offset:28160
	s_waitcnt lgkmcnt(14)
	v_mfma_f32_32x32x16_bf16 v[96:111], v[166:169], v[130:133], v[96:111]
	v_add_f32_e32 v14, v90, v14
	v_add_f32_e32 v14, v91, v14
	v_add_f32_e32 v14, v92, v14
	v_add_f32_e32 v14, v93, v14
	v_cvt_pk_bf16_f32 v146, v88, v89
	v_cvt_pk_bf16_f32 v147, v90, v91
	ds_read_b64_tr_b16 v[166:167], v0 offset:31744
	ds_read_b64_tr_b16 v[168:169], v0 offset:32256
	v_mfma_f32_32x32x16_bf16 v[114:129], v[162:165], v[130:133], v[114:129]
	v_add_f32_e32 v0, v94, v14
	v_add_f32_e32 v0, v95, v0
	v_add_f32_e32 v0, 0, v0
	v_cvt_pk_bf16_f32 v148, v92, v93
	v_cvt_pk_bf16_f32 v149, v94, v95
	s_add_i32 s7, s14, 5
	s_cmp_lt_i32 s7, s0
	s_cselect_b32 s2, s7, s12
	s_cmp_gt_i32 s7, s6
	s_cselect_b32 s9, s95, 0
	s_cselect_b32 s8, s13, 0
	s_lshl_b64 s[10:11], s[2:3], 18
	v_lshl_add_u64 v[14:15], v[214:215], 0, s[10:11]
	s_add_i32 s2, s15, s97
	v_lshl_add_u64 v[14:15], s[8:9], 1, v[14:15]
	s_mov_b32 s7, m0
	s_mov_b32 m0, s2
	s_nop 0
	global_load_lds_dwordx4 v[14:15], off
	s_mov_b32 m0, s7
	s_add_i32 s2, s14, 3
	s_cmp_ge_i32 s2, s0
	s_cselect_b64 s[34:35], -1, 0
	s_cmp_lt_i32 s2, s0
	s_cselect_b32 s2, s2, s12
	s_cmp_ge_i32 s90, s6
	s_cselect_b64 s[36:37], -1, 0
	s_cmp_lt_i32 s90, s6
	s_cselect_b32 s9, 0, s95
	s_cselect_b32 s8, 0, s13
	s_lshl_b64 s[10:11], s[2:3], 18
	v_lshl_add_u64 v[14:15], v[216:217], 0, s[10:11]
	s_add_i32 s2, s89, s92
	v_lshl_add_u64 v[14:15], s[8:9], 1, v[14:15]
	s_mov_b32 s7, m0
	s_mov_b32 m0, s2
	s_nop 0
	global_load_lds_dwordx4 v[14:15], off
	s_mov_b32 m0, s7
	s_cmp_gt_i32 s90, s6
	s_cselect_b64 s[8:9], -1, 0
	v_pk_add_f32 v[112:113], v[96:97], v[218:219] op_sel_hi:[1,0] neg_lo:[0,1] neg_hi:[0,1]
	v_pk_add_f32 v[96:97], v[114:115], v[218:219] op_sel_hi:[1,0] neg_lo:[0,1] neg_hi:[0,1]
	v_pk_add_f32 v[114:115], v[98:99], v[218:219] op_sel_hi:[1,0] neg_lo:[0,1] neg_hi:[0,1]
	v_pk_add_f32 v[98:99], v[116:117], v[218:219] op_sel_hi:[1,0] neg_lo:[0,1] neg_hi:[0,1]
	v_pk_add_f32 v[116:117], v[100:101], v[218:219] op_sel_hi:[1,0] neg_lo:[0,1] neg_hi:[0,1]
	v_pk_add_f32 v[100:101], v[118:119], v[218:219] op_sel_hi:[1,0] neg_lo:[0,1] neg_hi:[0,1]
	v_pk_add_f32 v[118:119], v[102:103], v[218:219] op_sel_hi:[1,0] neg_lo:[0,1] neg_hi:[0,1]
	v_pk_add_f32 v[102:103], v[120:121], v[218:219] op_sel_hi:[1,0] neg_lo:[0,1] neg_hi:[0,1]
	v_pk_add_f32 v[120:121], v[104:105], v[218:219] op_sel_hi:[1,0] neg_lo:[0,1] neg_hi:[0,1]
	v_pk_add_f32 v[104:105], v[122:123], v[218:219] op_sel_hi:[1,0] neg_lo:[0,1] neg_hi:[0,1]
	v_pk_add_f32 v[122:123], v[106:107], v[218:219] op_sel_hi:[1,0] neg_lo:[0,1] neg_hi:[0,1]
	v_pk_add_f32 v[106:107], v[124:125], v[218:219] op_sel_hi:[1,0] neg_lo:[0,1] neg_hi:[0,1]
	v_pk_add_f32 v[124:125], v[108:109], v[218:219] op_sel_hi:[1,0] neg_lo:[0,1] neg_hi:[0,1]
	v_pk_add_f32 v[108:109], v[126:127], v[218:219] op_sel_hi:[1,0] neg_lo:[0,1] neg_hi:[0,1]
	v_pk_add_f32 v[126:127], v[110:111], v[218:219] op_sel_hi:[1,0] neg_lo:[0,1] neg_hi:[0,1]
	v_pk_add_f32 v[110:111], v[128:129], v[218:219] op_sel_hi:[1,0] neg_lo:[0,1] neg_hi:[0,1]
	s_mov_b64 s[10:11], -1
	s_and_b64 vcc, exec, s[8:9]
	s_cbranch_vccnz .LBB0_1742
	s_add_i32 s2, s96, s14
	s_add_i32 s2, s2, 2
	s_cmp_lt_u32 s2, s93
	s_cselect_b64 s[10:11], -1, 0
	s_cmp_gt_u32 s2, s1
	s_cselect_b64 vcc, -1, 0
	s_or_b64 s[10:11], s[10:11], vcc
	s_and_b64 vcc, exec, s[10:11]
	s_cbranch_vccnz .LBB0_1740
	ds_read_b32 v14, v207 offset:128
	v_mov_b32_e32 v65, 0xc6ea6000
	v_mov_b32_e32 v64, 0xc6ea6000
	ds_read_b32 v235, v207
	ds_read_b32 v15, v207 offset:132
	ds_read_b32 v236, v207 offset:4
	ds_read_b32 v17, v207 offset:136
	v_mov_b32_e32 v67, 0xc6ea6000
	v_mov_b32_e32 v66, 0xc6ea6000
	ds_read_b32 v237, v207 offset:8
	ds_read_b32 v18, v207 offset:140
	ds_read_b32 v238, v207 offset:12
	ds_read_b32 v19, v207 offset:160
	v_mov_b32_e32 v69, 0xc6ea6000
	v_mov_b32_e32 v68, 0xc6ea6000
	ds_read_b32 v239, v207 offset:32
	ds_read_b32 v20, v207 offset:164
	ds_read_b32 v240, v207 offset:36
	ds_read_b32 v21, v207 offset:168
	v_mov_b32_e32 v71, 0xc6ea6000
	v_mov_b32_e32 v70, 0xc6ea6000
	ds_read_b32 v241, v207 offset:40
	ds_read_b32 v22, v207 offset:172
	ds_read_b32 v242, v207 offset:44
	s_waitcnt lgkmcnt(8)
	v_add_f32_e32 v251, v112, v235
	v_cndmask_b32_e64 v64, v64, v251, s[40:41]
	v_add_f32_e32 v251, v113, v236
	v_cndmask_b32_e64 v65, v65, v251, s[44:45]
	v_add_f32_e32 v251, v114, v237
	v_cndmask_b32_e64 v66, v66, v251, s[48:49]
	v_add_f32_e32 v251, v115, v238
	v_cndmask_b32_e64 v67, v67, v251, s[52:53]
	ds_read_b32 v23, v207 offset:192
	v_mov_b32_e32 v73, 0xc6ea6000
	v_mov_b32_e32 v72, 0xc6ea6000
	ds_read_b32 v243, v207 offset:64
	ds_read_b32 v24, v207 offset:196
	ds_read_b32 v244, v207 offset:68
	ds_read_b32 v25, v207 offset:200
	v_mov_b32_e32 v75, 0xc6ea6000
	v_mov_b32_e32 v74, 0xc6ea6000
	ds_read_b32 v245, v207 offset:72
	ds_read_b32 v26, v207 offset:204
	ds_read_b32 v246, v207 offset:76
	s_waitcnt lgkmcnt(8)
	v_add_f32_e32 v251, v116, v239
	v_cndmask_b32_e64 v68, v68, v251, s[56:57]
	v_add_f32_e32 v251, v117, v240
	v_cndmask_b32_e64 v69, v69, v251, s[60:61]
	v_add_f32_e32 v251, v118, v241
	v_cndmask_b32_e64 v70, v70, v251, s[64:65]
	v_add_f32_e32 v251, v119, v242
	v_cndmask_b32_e64 v71, v71, v251, s[68:69]
	ds_read_b32 v27, v207 offset:224
	v_mov_b32_e32 v77, 0xc6ea6000
	v_mov_b32_e32 v76, 0xc6ea6000
	ds_read_b32 v247, v207 offset:96
	ds_read_b32 v28, v207 offset:228
	ds_read_b32 v248, v207 offset:100
	ds_read_b32 v29, v207 offset:232
	v_mov_b32_e32 v79, 0xc6ea6000
	v_mov_b32_e32 v78, 0xc6ea6000
	ds_read_b32 v249, v207 offset:104
	ds_read_b32 v30, v207 offset:236
	ds_read_b32 v250, v207 offset:108
	s_waitcnt lgkmcnt(8)
	v_add_f32_e32 v251, v120, v243
	v_cndmask_b32_e64 v72, v72, v251, s[16:17]
	v_add_f32_e32 v251, v121, v244
	v_cndmask_b32_e64 v73, v73, v251, s[18:19]
	v_add_f32_e32 v251, v122, v245
	v_cndmask_b32_e64 v74, v74, v251, s[20:21]
	v_add_f32_e32 v251, v123, v246
	v_cndmask_b32_e64 v75, v75, v251, s[22:23]
	s_waitcnt lgkmcnt(14)
	v_add_f32_e32 v14, v96, v14
	v_cndmask_b32_e64 v80, v16, v14, s[42:43]
	v_add_f32_e32 v14, v97, v15
	v_cndmask_b32_e64 v81, v16, v14, s[46:47]
	s_waitcnt lgkmcnt(13)
	v_add_f32_e32 v14, v98, v17
	v_cndmask_b32_e64 v82, v16, v14, s[50:51]
	s_waitcnt lgkmcnt(12)
	v_add_f32_e32 v14, v99, v18
	v_cndmask_b32_e64 v83, v16, v14, s[54:55]
	s_waitcnt lgkmcnt(11)
	v_add_f32_e32 v14, v100, v19
	v_cndmask_b32_e64 v84, v16, v14, s[58:59]
	s_waitcnt lgkmcnt(10)
	v_add_f32_e32 v14, v101, v20
	v_cndmask_b32_e64 v85, v16, v14, s[62:63]
	s_waitcnt lgkmcnt(9)
	v_add_f32_e32 v14, v102, v21
	v_cndmask_b32_e64 v86, v16, v14, s[66:67]
	s_waitcnt lgkmcnt(8)
	v_add_f32_e32 v14, v103, v22
	v_cndmask_b32_e64 v87, v16, v14, s[70:71]
	s_waitcnt lgkmcnt(7)
	v_add_f32_e32 v14, v104, v23
	v_cndmask_b32_e64 v88, v16, v14, s[72:73]
	s_waitcnt lgkmcnt(6)
	v_add_f32_e32 v14, v105, v24
	v_cndmask_b32_e64 v89, v16, v14, s[74:75]
	s_waitcnt lgkmcnt(5)
	v_add_f32_e32 v14, v106, v25
	v_cndmask_b32_e64 v90, v16, v14, s[76:77]
	s_waitcnt lgkmcnt(4)
	v_add_f32_e32 v14, v107, v26
	v_cndmask_b32_e64 v91, v16, v14, s[78:79]
	s_waitcnt lgkmcnt(3)
	v_add_f32_e32 v14, v108, v27
	v_cndmask_b32_e64 v92, v16, v14, s[80:81]
	s_waitcnt lgkmcnt(2)
	v_add_f32_e32 v14, v109, v28
	v_cndmask_b32_e64 v93, v16, v14, s[82:83]
	s_waitcnt lgkmcnt(1)
	v_add_f32_e32 v14, v110, v29
	v_cndmask_b32_e64 v94, v16, v14, s[84:85]
	s_waitcnt lgkmcnt(0)
	v_add_f32_e32 v14, v111, v30
	v_cndmask_b32_e64 v95, v16, v14, s[86:87]
	v_add_f32_e32 v251, v124, v247
	v_cndmask_b32_e64 v76, v76, v251, s[24:25]
	v_add_f32_e32 v251, v125, v248
	v_cndmask_b32_e64 v77, v77, v251, s[26:27]
	v_add_f32_e32 v251, v126, v249
	v_cndmask_b32_e64 v78, v78, v251, s[28:29]
	v_add_f32_e32 v251, v127, v250
	v_cndmask_b32_e64 v79, v79, v251, s[30:31]
	s_branch .LBB0_1741

.LBB0_1753:
	s_add_i32 s2, s96, s14
	s_add_i32 s2, s2, 3
	s_cmp_lt_u32 s2, s93
	s_cselect_b64 s[8:9], -1, 0
	s_cmp_gt_u32 s2, s1
	s_cselect_b64 s[10:11], -1, 0
	s_or_b64 s[8:9], s[8:9], s[10:11]
	s_and_b64 vcc, exec, s[8:9]
	s_cbranch_vccnz .LBB0_1788
	ds_read_b32 v17, v207 offset:252
	v_mov_b32_e32 v65, 0xc6ea6000
	v_mov_b32_e32 v64, 0xc6ea6000
	ds_read_b32 v235, v207 offset:124
	ds_read_b32 v18, v207 offset:256
	ds_read_b32 v236, v207 offset:128
	ds_read_b32 v19, v207 offset:260
	v_mov_b32_e32 v67, 0xc6ea6000
	v_mov_b32_e32 v66, 0xc6ea6000
	ds_read_b32 v237, v207 offset:132
	ds_read_b32 v20, v207 offset:264
	ds_read_b32 v238, v207 offset:136
	ds_read_b32 v21, v207 offset:284
	v_mov_b32_e32 v69, 0xc6ea6000
	v_mov_b32_e32 v68, 0xc6ea6000
	ds_read_b32 v239, v207 offset:156
	ds_read_b32 v22, v207 offset:288
	ds_read_b32 v240, v207 offset:160
	ds_read_b32 v23, v207 offset:292
	v_mov_b32_e32 v71, 0xc6ea6000
	v_mov_b32_e32 v70, 0xc6ea6000
	ds_read_b32 v241, v207 offset:164
	ds_read_b32 v24, v207 offset:296
	ds_read_b32 v242, v207 offset:168
	s_waitcnt lgkmcnt(8)
	v_add_f32_e32 v251, v112, v235
	v_cndmask_b32_e64 v64, v64, v251, s[40:41]
	v_add_f32_e32 v251, v113, v236
	v_cndmask_b32_e64 v65, v65, v251, s[44:45]
	v_add_f32_e32 v251, v114, v237
	v_cndmask_b32_e64 v66, v66, v251, s[48:49]
	v_add_f32_e32 v251, v115, v238
	v_cndmask_b32_e64 v67, v67, v251, s[52:53]
	ds_read_b32 v25, v207 offset:316
	v_mov_b32_e32 v73, 0xc6ea6000
	v_mov_b32_e32 v72, 0xc6ea6000
	ds_read_b32 v243, v207 offset:188
	ds_read_b32 v26, v207 offset:320
	ds_read_b32 v244, v207 offset:192
	ds_read_b32 v27, v207 offset:324
	v_mov_b32_e32 v75, 0xc6ea6000
	v_mov_b32_e32 v74, 0xc6ea6000
	ds_read_b32 v245, v207 offset:196
	ds_read_b32 v28, v207 offset:328
	ds_read_b32 v246, v207 offset:200
	s_waitcnt lgkmcnt(8)
	v_add_f32_e32 v251, v116, v239
	v_cndmask_b32_e64 v68, v68, v251, s[56:57]
	v_add_f32_e32 v251, v117, v240
	v_cndmask_b32_e64 v69, v69, v251, s[60:61]
	v_add_f32_e32 v251, v118, v241
	v_cndmask_b32_e64 v70, v70, v251, s[64:65]
	v_add_f32_e32 v251, v119, v242
	v_cndmask_b32_e64 v71, v71, v251, s[68:69]
	ds_read_b32 v29, v207 offset:348
	v_mov_b32_e32 v77, 0xc6ea6000
	v_mov_b32_e32 v76, 0xc6ea6000
	ds_read_b32 v247, v207 offset:220
	ds_read_b32 v30, v207 offset:352
	ds_read_b32 v248, v207 offset:224
	ds_read_b32 v31, v207 offset:356
	v_mov_b32_e32 v79, 0xc6ea6000
	v_mov_b32_e32 v78, 0xc6ea6000
	ds_read_b32 v249, v207 offset:228
	ds_read_b32 v95, v207 offset:360
	ds_read_b32 v250, v207 offset:232
	s_waitcnt lgkmcnt(8)
	v_add_f32_e32 v251, v120, v243
	v_cndmask_b32_e64 v72, v72, v251, s[16:17]
	v_add_f32_e32 v251, v121, v244
	v_cndmask_b32_e64 v73, v73, v251, s[18:19]
	v_add_f32_e32 v251, v122, v245
	v_cndmask_b32_e64 v74, v74, v251, s[20:21]
	v_add_f32_e32 v251, v123, v246
	v_cndmask_b32_e64 v75, v75, v251, s[22:23]
	s_waitcnt lgkmcnt(14)
	v_add_f32_e32 v17, v96, v17
	v_cndmask_b32_e64 v80, v16, v17, s[42:43]
	v_add_f32_e32 v17, v97, v18
	v_cndmask_b32_e64 v81, v16, v17, s[46:47]
	s_waitcnt lgkmcnt(13)
	v_add_f32_e32 v17, v98, v19
	v_cndmask_b32_e64 v82, v16, v17, s[50:51]
	s_waitcnt lgkmcnt(12)
	v_add_f32_e32 v17, v99, v20
	v_cndmask_b32_e64 v83, v16, v17, s[54:55]
	s_waitcnt lgkmcnt(11)
	v_add_f32_e32 v17, v100, v21
	v_cndmask_b32_e64 v84, v16, v17, s[58:59]
	s_waitcnt lgkmcnt(10)
	v_add_f32_e32 v17, v101, v22
	v_cndmask_b32_e64 v85, v16, v17, s[62:63]
	s_waitcnt lgkmcnt(9)
	v_add_f32_e32 v17, v102, v23
	v_cndmask_b32_e64 v86, v16, v17, s[66:67]
	s_waitcnt lgkmcnt(8)
	v_add_f32_e32 v17, v103, v24
	v_cndmask_b32_e64 v87, v16, v17, s[70:71]
	s_waitcnt lgkmcnt(7)
	v_add_f32_e32 v17, v104, v25
	v_cndmask_b32_e64 v88, v16, v17, s[72:73]
	s_waitcnt lgkmcnt(6)
	v_add_f32_e32 v17, v105, v26
	v_cndmask_b32_e64 v89, v16, v17, s[74:75]
	s_waitcnt lgkmcnt(5)
	v_add_f32_e32 v17, v106, v27
	v_cndmask_b32_e64 v90, v16, v17, s[76:77]
	s_waitcnt lgkmcnt(4)
	v_add_f32_e32 v17, v107, v28
	v_cndmask_b32_e64 v91, v16, v17, s[78:79]
	s_waitcnt lgkmcnt(3)
	v_add_f32_e32 v17, v108, v29
	v_cndmask_b32_e64 v92, v16, v17, s[80:81]
	s_waitcnt lgkmcnt(2)
	v_add_f32_e32 v17, v109, v30
	v_cndmask_b32_e64 v93, v16, v17, s[82:83]
	s_waitcnt lgkmcnt(1)
	v_add_f32_e32 v17, v110, v31
	v_cndmask_b32_e64 v94, v16, v17, s[84:85]
	s_waitcnt lgkmcnt(0)
	v_add_f32_e32 v17, v111, v95
	v_cndmask_b32_e64 v95, v16, v17, s[86:87]
	v_add_f32_e32 v251, v124, v247
	v_cndmask_b32_e64 v76, v76, v251, s[24:25]
	v_add_f32_e32 v251, v125, v248
	v_cndmask_b32_e64 v77, v77, v251, s[26:27]
	v_add_f32_e32 v251, v126, v249
	v_cndmask_b32_e64 v78, v78, v251, s[28:29]
	v_add_f32_e32 v251, v127, v250
	v_cndmask_b32_e64 v79, v79, v251, s[30:31]
	s_branch .LBB0_1789
